# P6 fused-norm epilogue: norm-gain loads issued before the cross-workgroup row-statistics exchange instead of after it
# baseline (speedup 1.0000x reference)
.LBB0_724:
	s_or_b64 exec, exec, s[14:15]
	s_lshl_b32 s98, s0, 10
	s_ashr_i32 s99, s98, 31
	s_lshl_b64 s[98:99], s[98:99], 2
	v_readlane_b32 s96, v254, 34
	v_readlane_b32 s97, v254, 35
	s_add_u32 s98, s96, s98
	s_addc_u32 s99, s97, s99
	v_lshl_add_u64 v[236:237], v[144:145], 2, s[98:99]
	global_load_dwordx4 v[240:243], v[236:237], off offset:16
	global_load_dwordx4 v[244:247], v[236:237], off
	global_load_dwordx4 v[232:235], v[236:237], off offset:528
	global_load_dwordx4 v[236:239], v[236:237], off offset:512
	s_lshl_b32 s16, s0, 1
	s_ashr_i32 s17, s16, 31
	s_lshl_b64 s[14:15], s[16:17], 18
	s_add_u32 s4, s6, s14
	v_and_b32_e32 v128, 31, v142
	s_addc_u32 s9, s7, s15
	s_waitcnt lgkmcnt(0)
	s_barrier
	v_lshl_or_b32 v130, s2, 5, v128
	s_add_u32 s14, s4, 0xfd00000
	v_add_u32_e32 v128, s3, v130
	s_addc_u32 s15, s9, 0
	v_cmp_gt_u32_e64 s[38:39], 32, v132
	s_waitcnt lgkmcnt(0)
	v_ashrrev_i32_e32 v129, 31, v128
	s_and_saveexec_b64 s[18:19], s[38:39]
	s_cbranch_execz .LBB0_726
	v_lshl_add_u32 v131, v130, 4, 0
	ds_read_b128 v[134:137], v131
	s_ashr_i32 s13, s12, 31
	s_waitcnt lgkmcnt(0)
	v_mov_b32_e32 v138, v135
	v_mov_b32_e32 v139, v136
	v_mov_b32_e32 v135, v137
	v_pk_add_f32 v[134:135], v[138:139], v[134:135]
	v_lshl_add_u64 v[136:137], v[128:129], 4, s[14:15]
	v_pk_add_f32 v[134:135], v[134:135], v[134:135] op_sel:[0,1] op_sel_hi:[1,0]
	v_lshl_add_u64 v[136:137], s[12:13], 2, v[136:137]
	global_store_dword v[136:137], v134, off sc1

.LBB0_737:
	s_or_b64 exec, exec, s[8:9]
	s_lshl_b32 s0, s0, 10
	s_ashr_i32 s1, s0, 31
	v_readlane_b32 s12, v254, 26
	s_lshl_b64 s[0:1], s[0:1], 2
	v_readlane_b32 s20, v254, 34
	v_readlane_b32 s21, v254, 35
	s_add_u32 s0, s20, s0
	s_addc_u32 s1, s21, s1
	s_waitcnt vmcnt(0) lgkmcnt(0)
	s_barrier
	v_lshl_add_u32 v149, v146, 2, 0
	ds_read_b32 v150, v149 offset:8192
	v_add_u32_e32 v146, s3, v146
	s_add_u32 s6, s6, 0xae00000
	v_ashrrev_i32_e32 v147, 31, v146
	s_addc_u32 s7, s7, 0
	s_waitcnt lgkmcnt(0)
	v_pk_mul_f32 v[68:69], v[68:69], v[150:151] op_sel_hi:[1,0]
	v_pk_mul_f32 v[70:71], v[70:71], v[150:151] op_sel_hi:[1,0]
	v_pk_mul_f32 v[64:65], v[64:65], v[150:151] op_sel_hi:[1,0]
	v_lshlrev_b64 v[152:153], 11, v[146:147]
	v_pk_mul_f32 v[66:67], v[66:67], v[150:151] op_sel_hi:[1,0]
	v_readlane_b32 s13, v254, 27
	v_readlane_b32 s14, v254, 28
	v_readlane_b32 s15, v254, 29
	v_readlane_b32 s16, v254, 30
	v_readlane_b32 s17, v254, 31
	v_readlane_b32 s18, v254, 32
	v_readlane_b32 s19, v254, 33
	v_readlane_b32 s22, v254, 36
	v_readlane_b32 s23, v254, 37
	v_readlane_b32 s24, v254, 38
	v_readlane_b32 s25, v254, 39
	v_readlane_b32 s26, v254, 40
	v_readlane_b32 s27, v254, 41
	s_waitcnt vmcnt(3)
	v_pk_mul_f32 v[64:65], v[240:241], v[64:65]
	s_waitcnt vmcnt(2)
	v_pk_mul_f32 v[70:71], v[246:247], v[70:71]
	v_pk_mul_f32 v[68:69], v[244:245], v[68:69]
	v_pk_mul_f32 v[154:155], v[242:243], v[66:67]
	v_cvt_pk_bf16_f32 v66, v68, v69
	v_cvt_pk_bf16_f32 v67, v70, v71
	v_cvt_pk_bf16_f32 v68, v64, v65
	v_lshl_add_u64 v[70:71], s[6:7], 0, v[152:153]
	v_lshlrev_b64 v[64:65], 1, v[144:145]
	v_cvt_pk_bf16_f32 v69, v154, v155
	v_lshl_add_u64 v[70:71], v[70:71], 0, v[64:65]
	global_store_dwordx4 v[70:71], v[66:69], off
	s_nop 1
	v_pk_mul_f32 v[66:67], v[96:97], v[150:151] op_sel_hi:[1,0]
	v_pk_mul_f32 v[68:69], v[98:99], v[150:151] op_sel_hi:[1,0]
	s_waitcnt vmcnt(1)
	v_pk_mul_f32 v[66:67], v[236:237], v[66:67]
	v_pk_mul_f32 v[68:69], v[238:239], v[68:69]
	v_pk_mul_f32 v[96:97], v[100:101], v[150:151] op_sel_hi:[1,0]
	v_pk_mul_f32 v[98:99], v[102:103], v[150:151] op_sel_hi:[1,0]
	v_pk_mul_f32 v[96:97], v[232:233], v[96:97]
	v_pk_mul_f32 v[98:99], v[234:235], v[98:99]
	v_cvt_pk_bf16_f32 v66, v66, v67
	v_cvt_pk_bf16_f32 v67, v68, v69
	v_cvt_pk_bf16_f32 v68, v96, v97
	s_nop 0
	v_cvt_pk_bf16_f32 v69, v98, v99
	global_store_dwordx4 v[70:71], v[66:69], off offset:256
	ds_read_b32 v70, v149 offset:8256
	s_waitcnt lgkmcnt(0)
	v_pk_mul_f32 v[98:99], v[108:109], v[70:71] op_sel_hi:[1,0]
	v_add_u32_e32 v66, 16, v146
	v_ashrrev_i32_e32 v67, 31, v66
	v_lshlrev_b64 v[96:97], 11, v[66:67]
	v_pk_mul_f32 v[66:67], v[112:113], v[70:71] op_sel_hi:[1,0]
	v_pk_mul_f32 v[68:69], v[114:115], v[70:71] op_sel_hi:[1,0]
	v_pk_mul_f32 v[66:67], v[244:245], v[66:67]
	v_lshl_add_u64 v[96:97], s[6:7], 0, v[96:97]
	v_pk_mul_f32 v[68:69], v[246:247], v[68:69]
	v_pk_mul_f32 v[100:101], v[110:111], v[70:71] op_sel_hi:[1,0]
	v_cvt_pk_bf16_f32 v66, v66, v67
	v_cvt_pk_bf16_f32 v67, v68, v69
	v_lshl_add_u64 v[96:97], v[96:97], 0, v[64:65]
	v_pk_mul_f32 v[100:101], v[242:243], v[100:101]
	v_pk_mul_f32 v[98:99], v[240:241], v[98:99]
	s_nop 0
	v_cvt_pk_bf16_f32 v68, v98, v99
	v_cvt_pk_bf16_f32 v69, v100, v101
	global_store_dwordx4 v[96:97], v[66:69], off
	v_pk_mul_f32 v[98:99], v[124:125], v[70:71] op_sel_hi:[1,0]
	s_nop 0
	v_pk_mul_f32 v[66:67], v[120:121], v[70:71] op_sel_hi:[1,0]
	v_pk_mul_f32 v[68:69], v[122:123], v[70:71] op_sel_hi:[1,0]
	v_pk_mul_f32 v[66:67], v[236:237], v[66:67]
	v_pk_mul_f32 v[68:69], v[238:239], v[68:69]
	v_pk_mul_f32 v[70:71], v[126:127], v[70:71] op_sel_hi:[1,0]
	v_cvt_pk_bf16_f32 v66, v66, v67
	v_pk_mul_f32 v[98:99], v[232:233], v[98:99]
	v_pk_mul_f32 v[70:71], v[234:235], v[70:71]
	v_cvt_pk_bf16_f32 v67, v68, v69
	v_cvt_pk_bf16_f32 v68, v98, v99
	s_nop 0
	v_cvt_pk_bf16_f32 v69, v70, v71
	global_store_dwordx4 v[96:97], v[66:69], off offset:256
	ds_read_b32 v66, v149 offset:8320
	s_waitcnt lgkmcnt(0)
	v_pk_mul_f32 v[70:71], v[78:79], v[66:67] op_sel_hi:[1,0]
	v_add_u32_e32 v68, 32, v146
	v_ashrrev_i32_e32 v69, 31, v68
	v_lshlrev_b64 v[96:97], 11, v[68:69]
	v_pk_mul_f32 v[68:69], v[76:77], v[66:67] op_sel_hi:[1,0]
	v_pk_mul_f32 v[72:73], v[72:73], v[66:67] op_sel_hi:[1,0]
	v_pk_mul_f32 v[70:71], v[246:247], v[70:71]
	v_pk_mul_f32 v[68:69], v[244:245], v[68:69]
	v_pk_mul_f32 v[72:73], v[240:241], v[72:73]
	v_pk_mul_f32 v[74:75], v[74:75], v[66:67] op_sel_hi:[1,0]
	v_cvt_pk_bf16_f32 v68, v68, v69
	v_cvt_pk_bf16_f32 v69, v70, v71
	v_cvt_pk_bf16_f32 v70, v72, v73
	v_lshl_add_u64 v[72:73], s[6:7], 0, v[96:97]
	v_pk_mul_f32 v[74:75], v[242:243], v[74:75]
	v_lshl_add_u64 v[72:73], v[72:73], 0, v[64:65]
	v_cvt_pk_bf16_f32 v71, v74, v75
	global_store_dwordx4 v[72:73], v[68:71], off
	v_pk_mul_f32 v[74:75], v[80:81], v[66:67] op_sel_hi:[1,0]
	s_nop 0
	v_pk_mul_f32 v[68:69], v[84:85], v[66:67] op_sel_hi:[1,0]
	v_pk_mul_f32 v[70:71], v[86:87], v[66:67] op_sel_hi:[1,0]
	v_pk_mul_f32 v[68:69], v[236:237], v[68:69]
	v_pk_mul_f32 v[70:71], v[238:239], v[70:71]
	v_pk_mul_f32 v[66:67], v[82:83], v[66:67] op_sel_hi:[1,0]
	v_pk_mul_f32 v[74:75], v[232:233], v[74:75]
	v_pk_mul_f32 v[76:77], v[234:235], v[66:67]
	v_cvt_pk_bf16_f32 v66, v68, v69
	v_cvt_pk_bf16_f32 v67, v70, v71
	v_cvt_pk_bf16_f32 v68, v74, v75
	s_nop 0
	v_cvt_pk_bf16_f32 v69, v76, v77
	ds_read_b32 v70, v149 offset:8384
	global_store_dwordx4 v[72:73], v[66:69], off offset:256
	s_waitcnt lgkmcnt(0)
	v_pk_mul_f32 v[74:75], v[88:89], v[70:71] op_sel_hi:[1,0]
	v_add_u32_e32 v66, 48, v146
	v_ashrrev_i32_e32 v67, 31, v66
	v_lshlrev_b64 v[72:73], 11, v[66:67]
	v_pk_mul_f32 v[66:67], v[92:93], v[70:71] op_sel_hi:[1,0]
	v_pk_mul_f32 v[68:69], v[94:95], v[70:71] op_sel_hi:[1,0]
	v_pk_mul_f32 v[66:67], v[244:245], v[66:67]
	v_lshl_add_u64 v[72:73], s[6:7], 0, v[72:73]
	v_pk_mul_f32 v[68:69], v[246:247], v[68:69]
	v_pk_mul_f32 v[76:77], v[90:91], v[70:71] op_sel_hi:[1,0]
	v_cvt_pk_bf16_f32 v66, v66, v67
	v_cvt_pk_bf16_f32 v67, v68, v69
	v_lshl_add_u64 v[72:73], v[72:73], 0, v[64:65]
	v_pk_mul_f32 v[76:77], v[242:243], v[76:77]
	v_pk_mul_f32 v[74:75], v[240:241], v[74:75]
	s_nop 0
	v_cvt_pk_bf16_f32 v68, v74, v75
	v_cvt_pk_bf16_f32 v69, v76, v77
	global_store_dwordx4 v[72:73], v[66:69], off
	v_pk_mul_f32 v[74:75], v[104:105], v[70:71] op_sel_hi:[1,0]
	s_nop 0
	v_pk_mul_f32 v[66:67], v[116:117], v[70:71] op_sel_hi:[1,0]
	v_pk_mul_f32 v[68:69], v[118:119], v[70:71] op_sel_hi:[1,0]
	v_pk_mul_f32 v[66:67], v[236:237], v[66:67]
	v_pk_mul_f32 v[68:69], v[238:239], v[68:69]
	v_pk_mul_f32 v[70:71], v[106:107], v[70:71] op_sel_hi:[1,0]
	v_cvt_pk_bf16_f32 v66, v66, v67
	v_pk_mul_f32 v[74:75], v[232:233], v[74:75]
	v_pk_mul_f32 v[70:71], v[234:235], v[70:71]
	v_cvt_pk_bf16_f32 v67, v68, v69
	v_cvt_pk_bf16_f32 v68, v74, v75
	s_nop 0
	v_cvt_pk_bf16_f32 v69, v70, v71
	global_store_dwordx4 v[72:73], v[66:69], off offset:256
	ds_read_b32 v66, v149 offset:8704
	s_waitcnt lgkmcnt(0)
	v_pk_mul_f32 v[60:61], v[60:61], v[66:67] op_sel_hi:[1,0]
	v_add_u32_e32 v68, s3, v148
	v_ashrrev_i32_e32 v69, 31, v68
	v_lshlrev_b64 v[68:69], 11, v[68:69]
	v_pk_mul_f32 v[60:61], v[244:245], v[60:61]
	v_pk_mul_f32 v[56:57], v[56:57], v[66:67] op_sel_hi:[1,0]
	v_pk_mul_f32 v[58:59], v[58:59], v[66:67] op_sel_hi:[1,0]
	v_pk_mul_f32 v[62:63], v[62:63], v[66:67] op_sel_hi:[1,0]
	v_pk_mul_f32 v[70:71], v[242:243], v[58:59]
	v_pk_mul_f32 v[58:59], v[240:241], v[56:57]
	v_cvt_pk_bf16_f32 v56, v60, v61
	v_lshl_add_u64 v[60:61], s[6:7], 0, v[68:69]
	v_pk_mul_f32 v[62:63], v[246:247], v[62:63]
	v_lshl_add_u64 v[60:61], v[60:61], 0, v[64:65]
	v_cvt_pk_bf16_f32 v57, v62, v63
	v_pk_mul_f32 v[52:53], v[52:53], v[66:67] op_sel_hi:[1,0]
	v_pk_mul_f32 v[48:49], v[48:49], v[66:67] op_sel_hi:[1,0]
	v_pk_mul_f32 v[50:51], v[50:51], v[66:67] op_sel_hi:[1,0]
	v_cvt_pk_bf16_f32 v58, v58, v59
	v_cvt_pk_bf16_f32 v59, v70, v71
	global_store_dwordx4 v[60:61], v[56:59], off
	v_pk_mul_f32 v[54:55], v[54:55], v[66:67] op_sel_hi:[1,0]
	v_pk_mul_f32 v[52:53], v[236:237], v[52:53]
	v_pk_mul_f32 v[56:57], v[234:235], v[50:51]
	v_pk_mul_f32 v[50:51], v[232:233], v[48:49]
	v_cvt_pk_bf16_f32 v48, v52, v53
	v_pk_mul_f32 v[54:55], v[238:239], v[54:55]
	s_nop 0
	v_cvt_pk_bf16_f32 v49, v54, v55
	v_cvt_pk_bf16_f32 v50, v50, v51
	v_cvt_pk_bf16_f32 v51, v56, v57
	global_store_dwordx4 v[60:61], v[48:51], off offset:256
	ds_read_b32 v48, v149 offset:8768
	s_waitcnt lgkmcnt(0)
	v_pk_mul_f32 v[44:45], v[44:45], v[48:49] op_sel_hi:[1,0]
	v_add_u32_e32 v50, 0x90, v146
	v_ashrrev_i32_e32 v51, 31, v50
	v_lshlrev_b64 v[50:51], 11, v[50:51]
	v_pk_mul_f32 v[44:45], v[244:245], v[44:45]
	v_pk_mul_f32 v[40:41], v[40:41], v[48:49] op_sel_hi:[1,0]
	v_pk_mul_f32 v[42:43], v[42:43], v[48:49] op_sel_hi:[1,0]
	v_pk_mul_f32 v[46:47], v[46:47], v[48:49] op_sel_hi:[1,0]
	v_pk_mul_f32 v[52:53], v[242:243], v[42:43]
	v_pk_mul_f32 v[42:43], v[240:241], v[40:41]
	v_cvt_pk_bf16_f32 v40, v44, v45
	v_lshl_add_u64 v[44:45], s[6:7], 0, v[50:51]
	v_pk_mul_f32 v[46:47], v[246:247], v[46:47]
	v_lshl_add_u64 v[44:45], v[44:45], 0, v[64:65]
	v_cvt_pk_bf16_f32 v41, v46, v47
	v_pk_mul_f32 v[36:37], v[36:37], v[48:49] op_sel_hi:[1,0]
	v_pk_mul_f32 v[32:33], v[32:33], v[48:49] op_sel_hi:[1,0]
	v_pk_mul_f32 v[34:35], v[34:35], v[48:49] op_sel_hi:[1,0]
	v_cvt_pk_bf16_f32 v42, v42, v43
	v_cvt_pk_bf16_f32 v43, v52, v53
	global_store_dwordx4 v[44:45], v[40:43], off
	v_pk_mul_f32 v[38:39], v[38:39], v[48:49] op_sel_hi:[1,0]
	v_pk_mul_f32 v[36:37], v[236:237], v[36:37]
	v_pk_mul_f32 v[40:41], v[234:235], v[34:35]
	v_pk_mul_f32 v[34:35], v[232:233], v[32:33]
	v_cvt_pk_bf16_f32 v32, v36, v37
	v_pk_mul_f32 v[38:39], v[238:239], v[38:39]
	s_nop 0
	v_cvt_pk_bf16_f32 v33, v38, v39
	v_cvt_pk_bf16_f32 v34, v34, v35
	v_cvt_pk_bf16_f32 v35, v40, v41
	global_store_dwordx4 v[44:45], v[32:35], off offset:256
	ds_read_b32 v32, v149 offset:8832
	s_waitcnt lgkmcnt(0)
	v_pk_mul_f32 v[28:29], v[28:29], v[32:33] op_sel_hi:[1,0]
	v_add_u32_e32 v34, 0xa0, v146
	v_ashrrev_i32_e32 v35, 31, v34
	v_lshlrev_b64 v[34:35], 11, v[34:35]
	v_pk_mul_f32 v[28:29], v[244:245], v[28:29]
	v_pk_mul_f32 v[24:25], v[24:25], v[32:33] op_sel_hi:[1,0]
	v_pk_mul_f32 v[26:27], v[26:27], v[32:33] op_sel_hi:[1,0]
	v_pk_mul_f32 v[30:31], v[30:31], v[32:33] op_sel_hi:[1,0]
	v_pk_mul_f32 v[36:37], v[242:243], v[26:27]
	v_pk_mul_f32 v[26:27], v[240:241], v[24:25]
	v_cvt_pk_bf16_f32 v24, v28, v29
	v_lshl_add_u64 v[28:29], s[6:7], 0, v[34:35]
	v_pk_mul_f32 v[30:31], v[246:247], v[30:31]
	v_lshl_add_u64 v[28:29], v[28:29], 0, v[64:65]
	v_cvt_pk_bf16_f32 v25, v30, v31
	v_pk_mul_f32 v[20:21], v[20:21], v[32:33] op_sel_hi:[1,0]
	v_pk_mul_f32 v[16:17], v[16:17], v[32:33] op_sel_hi:[1,0]
	v_pk_mul_f32 v[18:19], v[18:19], v[32:33] op_sel_hi:[1,0]
	v_cvt_pk_bf16_f32 v26, v26, v27
	v_cvt_pk_bf16_f32 v27, v36, v37
	global_store_dwordx4 v[28:29], v[24:27], off
	v_pk_mul_f32 v[22:23], v[22:23], v[32:33] op_sel_hi:[1,0]
	v_pk_mul_f32 v[20:21], v[236:237], v[20:21]
	v_pk_mul_f32 v[24:25], v[234:235], v[18:19]
	v_pk_mul_f32 v[18:19], v[232:233], v[16:17]
	v_cvt_pk_bf16_f32 v16, v20, v21
	v_pk_mul_f32 v[22:23], v[238:239], v[22:23]
	s_nop 0
	v_cvt_pk_bf16_f32 v17, v22, v23
	v_cvt_pk_bf16_f32 v18, v18, v19
	v_cvt_pk_bf16_f32 v19, v24, v25
	global_store_dwordx4 v[28:29], v[16:19], off offset:256
	ds_read_b32 v16, v149 offset:8896
	s_waitcnt lgkmcnt(0)
	v_pk_mul_f32 v[12:13], v[12:13], v[16:17] op_sel_hi:[1,0]
	v_add_u32_e32 v18, 0xb0, v146
	v_ashrrev_i32_e32 v19, 31, v18
	v_lshlrev_b64 v[18:19], 11, v[18:19]
	v_pk_mul_f32 v[12:13], v[244:245], v[12:13]
	v_pk_mul_f32 v[8:9], v[8:9], v[16:17] op_sel_hi:[1,0]
	v_pk_mul_f32 v[10:11], v[10:11], v[16:17] op_sel_hi:[1,0]
	v_pk_mul_f32 v[14:15], v[14:15], v[16:17] op_sel_hi:[1,0]
	v_pk_mul_f32 v[20:21], v[242:243], v[10:11]
	v_pk_mul_f32 v[10:11], v[240:241], v[8:9]
	v_cvt_pk_bf16_f32 v8, v12, v13
	v_lshl_add_u64 v[12:13], s[6:7], 0, v[18:19]
	v_pk_mul_f32 v[14:15], v[246:247], v[14:15]
	v_lshl_add_u64 v[12:13], v[12:13], 0, v[64:65]
	v_cvt_pk_bf16_f32 v9, v14, v15
	v_pk_mul_f32 v[0:1], v[0:1], v[16:17] op_sel_hi:[1,0]
	v_pk_mul_f32 v[2:3], v[2:3], v[16:17] op_sel_hi:[1,0]
	v_cvt_pk_bf16_f32 v10, v10, v11
	v_cvt_pk_bf16_f32 v11, v20, v21
	global_store_dwordx4 v[12:13], v[8:11], off
	v_pk_mul_f32 v[4:5], v[4:5], v[16:17] op_sel_hi:[1,0]
	v_pk_mul_f32 v[6:7], v[6:7], v[16:17] op_sel_hi:[1,0]
	v_pk_mul_f32 v[8:9], v[234:235], v[2:3]
	v_pk_mul_f32 v[2:3], v[232:233], v[0:1]
	v_pk_mul_f32 v[6:7], v[238:239], v[6:7]
	v_pk_mul_f32 v[4:5], v[236:237], v[4:5]
	s_nop 0
	v_cvt_pk_bf16_f32 v0, v4, v5
	v_cvt_pk_bf16_f32 v1, v6, v7
	v_cvt_pk_bf16_f32 v2, v2, v3
	v_cvt_pk_bf16_f32 v3, v8, v9
	global_store_dwordx4 v[12:13], v[0:3], off offset:256
